# scan: L2 prefetch of the next chunk's C and B tiles from l-tile 5 of the y pass (two LDS-DMA dword loads per wave into an unused LDS line), counted wait adjusted
# speedup vs baseline: 1.0081x; 1.0022x over previous
; #define LAS __attribute__((address_space(3)))
;     __device__ __forceinline__ const char* b(const pg8::Unit& u) const { return (const char*)ws + boff + (size_t)u.pn * 256 * K_ * 2 + (u.kq < 0 ? 0 : u.kq * (K_ / 4) * 2); }
; template <int MODE> __device__ __forceinline__ void ssd_scan_phase(Frame& F, int j, bool ctx_out) {
;     ...
; #pragma unroll
;                     for (int q = 0; q < 4; ++q) {
;                         const u32x2 lo = *(const LAS u32x2*)(CS + l * 256 + (((4 * q + (fq >> 1)) ^ fr) << 4) + (fq & 1) * 8), hi = *(const LAS u32x2*)(CS + l * 256 + (((4 * q + 2 + (fq >> 1)) ^ fr) << 4) + (fq & 1) * 8);
;                         u32x4 c4; c4.x = lo.x; c4.y = lo.y; c4.z = hi.x; c4.w = hi.y; const bf16x8 cfr = __builtin_bit_cast(bf16x8, c4);
;                         acco[0] = __builtin_amdgcn_mfma_f32_16x16x32_bf16(hf[0][q], cfr, acco[0], 0, 0, 0);
;                         acco[1] = __builtin_amdgcn_mfma_f32_16x16x32_bf16(hf[1][q], cfr, acco[1], 0, 0, 0);
;                     }
;                     {
;                         float gg[8]; unpack8(*(const LAS u32x4*)(GS + l * 256 + (((4 * kd + fq) ^ fr) << 4)), gg);
;                         const f32x4 ca = *(const LAS f32x4*)(tab + 32 * kd + 8 * fq), cb = *(const LAS f32x4*)(tab + 32 * kd + 8 * fq + 4);
;                         const f32x4 da = *(const LAS f32x4*)(tab + 128 + 32 * kd + 8 * fq), db = *(const LAS f32x4*)(tab + 128 + 32 * kd + 8 * fq + 4);
;                         const float cs[8] = {ca.x, ca.y, ca.z, ca.w, cb.x, cb.y, cb.z, cb.w}, ds[8] = {da.x, da.y, da.z, da.w, db.x, db.y, db.z, db.w};
;                         float m[8];
; #pragma unroll
;                         for (int jj = 0; jj < 8; ++jj) { const int s = 32 * kd + 8 * fq + jj; const bool valid = dir == 0 ? (s <= l) : (s >= l);
;                             const float e = valid ? __builtin_amdgcn_exp2f(cl - cs[jj]) : 0.f; m[jj] = gg[jj] * e * ds[jj]; if (dir == 0 && s == l) m[jj] += dsk; }
;     ...
;                 const int kn = k + 1; const bool isctxn = kn < 2; const int ccn = isctxn ? (dir == 0 ? kn : 1 - kn) : (dir == 0 ? kn - 2 : 17 - kn);
;                 const int row0n = isctxn ? MLAT + b * LCTX + ccn * 128 : b * LSEQ + ccn * 128;
;                 if ((ctx_out || !isctxn) && !(MODE & 8)) { SCAN_DMA(CS, cm + (size_t)row0n * GNW + g * 128, GNW); SCAN_DMA(GS, bm + (size_t)row0n * GNW + g * 128, GNW); }
.LBB0_514:
	v_mbcnt_lo_u32_b32 v179, -1, 0
	v_mbcnt_hi_u32_b32 v179, -1, v179
	s_sub_i32 s100, s4, 1
	s_sub_i32 s101, 16, s4
	s_cmp_lg_u32 s38, 0
	s_cselect_b32 s100, s100, s101
	v_and_b32_e32 v178, 3, v179
	s_lshl_b32 s100, s100, 7
	s_add_i32 s100, s100, s81
	s_cmp_eq_u32 s4, 0
	s_cselect_b32 s100, s76, s100
	s_cmp_eq_u32 s4, 17
	s_cselect_b32 s100, s81, s100
	v_lshl_add_u32 v178, v178, 5, v188
	v_and_b32_e32 v179, 4, v179
	s_lshl_b32 s100, s100, 11
	v_lshlrev_b32_e32 v178, 11, v178
	v_lshl_add_u32 v178, v179, 5, v178
	s_mov_b32 m0, 0x1c000
	v_add_u32_e32 v178, s100, v178
	s_mov_b32 s100, s77
	s_mov_b32 s101, s73
	global_load_lds_dword v178, s[100:101]
	global_load_lds_dword v178, s[74:75]
	v_add3_u32 v178, 0, v218, v195
	v_add_u32_e32 v179, v178, v185
	ds_read_b64 v[218:219], v179
	v_add_u32_e32 v179, v178, v183
	ds_read_b64 v[220:221], v179
	v_add_u32_e32 v179, v178, v187
	ds_read_b64 v[226:227], v179
	v_add_u32_e32 v179, v178, v213
	ds_read_b64 v[228:229], v179
	s_waitcnt lgkmcnt(2)
	v_mfma_f32_16x16x32_bf16 v[222:225], v[116:119], v[218:221], 0
	v_add_u32_e32 v179, v178, v212
	ds_read_b64 v[230:231], v179
	v_add_u32_e32 v179, v178, v211
	v_mfma_f32_16x16x32_bf16 v[218:221], v[124:127], v[218:221], 0
	ds_read_b64 v[232:233], v179
	v_add_u32_e32 v179, v178, v191
	v_add_u32_e32 v178, v178, v210
	s_waitcnt lgkmcnt(2)
	v_mfma_f32_16x16x32_bf16 v[222:225], v[112:115], v[226:229], v[222:225]
	v_add_u32_e32 v170, v170, v168
	v_sub_f32_e32 v164, v171, v164
	v_exp_f32_e32 v164, v164
	v_mfma_f32_16x16x32_bf16 v[218:221], v[120:123], v[226:229], v[218:221]
	ds_read_b64 v[226:227], v179
	ds_read_b64 v[228:229], v178
	v_sub_f32_e32 v165, v171, v165
	s_waitcnt lgkmcnt(2)
	v_mfma_f32_16x16x32_bf16 v[222:225], v[108:111], v[230:233], v[222:225]
	v_exp_f32_e32 v165, v165
	v_sub_f32_e32 v166, v171, v166
	v_exp_f32_e32 v166, v166
	v_mfma_f32_16x16x32_bf16 v[218:221], v[128:131], v[230:233], v[218:221]
	ds_read_b128 v[230:233], v170
	v_add_u32_e32 v170, 64, v180
	s_waitcnt lgkmcnt(1)
	v_mfma_f32_16x16x32_bf16 v[222:225], v[104:107], v[226:229], v[222:225]
	s_waitcnt lgkmcnt(0)
; #define LAS __attribute__((address_space(3)))
; __device__ __forceinline__ unsigned cvt_pk_bf16(float lo, float hi) { const f32x2 v = {lo, hi}; return __builtin_bit_cast(unsigned, __builtin_convertvector(v, bf16x2_t)); }
; __device__ __forceinline__ u32x4 pack8(const float (&f)[8]) { u32x4 w; w.x = cvt_pk_bf16(f[0], f[1]); w.y = cvt_pk_bf16(f[2], f[3]); w.z = cvt_pk_bf16(f[4], f[5]); w.w = cvt_pk_bf16(f[6], f[7]); return w; }
; template <int MODE> __device__ __forceinline__ void ssd_scan_phase(Frame& F, int j, bool ctx_out) {
;     ...
;                         float gg[8]; unpack8(*(const LAS u32x4*)(GS + l * 256 + (((4 * kd + fq) ^ fr) << 4)), gg);
;                         const f32x4 ca = *(const LAS f32x4*)(tab + 32 * kd + 8 * fq), cb = *(const LAS f32x4*)(tab + 32 * kd + 8 * fq + 4);
;                         const f32x4 da = *(const LAS f32x4*)(tab + 128 + 32 * kd + 8 * fq), db = *(const LAS f32x4*)(tab + 128 + 32 * kd + 8 * fq + 4);
;                         const float cs[8] = {ca.x, ca.y, ca.z, ca.w, cb.x, cb.y, cb.z, cb.w}, ds[8] = {da.x, da.y, da.z, da.w, db.x, db.y, db.z, db.w};
;                         float m[8];
; #pragma unroll
;                         for (int jj = 0; jj < 8; ++jj) { const int s = 32 * kd + 8 * fq + jj; const bool valid = dir == 0 ? (s <= l) : (s >= l);
;                             const float e = valid ? __builtin_amdgcn_exp2f(cl - cs[jj]) : 0.f; m[jj] = gg[jj] * e * ds[jj]; if (dir == 0 && s == l) m[jj] += dsk; }
;                         const bf16x8 mf = __builtin_bit_cast(bf16x8, pack8(m));
;                         accd[0] = __builtin_amdgcn_mfma_f32_16x16x32_bf16(xa, mf, accd[0], 0, 0, 0);
;                         accd[1] = __builtin_amdgcn_mfma_f32_16x16x32_bf16(xb, mf, accd[1], 0, 0, 0);
;                     }
;                     const float el = __builtin_amdgcn_exp2f(cl);
; #pragma unroll
;                     for (int pt = 0; pt < 2; ++pt) { const f32x4 y = accd[pt] + acco[pt] * el; u32x2 o; o.x = cvt_pk_bf16(y[0], y[1]); o.y = cvt_pk_bf16(y[2], y[3]);
;                         *(u32x2*)(yout + (size_t)(row0 + l) * DI + h * 64 + ph * 32 + 16 * pt + 4 * fq) = o; }
	v_lshlrev_b32_e32 v178, 16, v230
	v_and_b32_e32 v179, 0xffff0000, v230
	v_lshlrev_b32_e32 v230, 16, v233
	v_mfma_f32_16x16x32_bf16 v[218:221], v[132:135], v[226:229], v[218:221]
	v_lshlrev_b32_e32 v226, 16, v231
	v_and_b32_e32 v227, 0xffff0000, v231
	v_lshlrev_b32_e32 v228, 16, v232
	v_and_b32_e32 v229, 0xffff0000, v232
	v_and_b32_e32 v231, 0xffff0000, v233
	v_cmp_le_i32_e32 vcc, v170, v169
	v_cmp_eq_u32_e64 s[100:101], v170, v169
	s_xnor_b64 vcc, vcc, s[38:39]
	s_andn2_b64 s[100:101], s[100:101], s[38:39]
	s_or_b64 vcc, vcc, s[100:101]
	v_sub_f32_e32 v156, v171, v156
	v_cndmask_b32_e32 v164, 0, v164, vcc
	v_mul_f32_e32 v164, v164, v178
	v_cmp_eq_u32_e32 vcc, v170, v169
	v_mul_f32_e32 v178, v160, v164
	s_and_b64 vcc, s[38:39], vcc
	v_fma_f32 v160, v160, v164, v203
	v_cndmask_b32_e32 v160, v178, v160, vcc
	v_cmp_le_i32_e32 vcc, v173, v169
	v_cmp_eq_u32_e64 s[100:101], v173, v169
	s_xnor_b64 vcc, vcc, s[38:39]
	s_andn2_b64 s[100:101], s[100:101], s[38:39]
	s_or_b64 vcc, vcc, s[100:101]
	v_exp_f32_e32 v156, v156
	v_sub_f32_e32 v157, v171, v157
	v_cndmask_b32_e32 v164, 0, v165, vcc
	v_mul_f32_e32 v164, v164, v179
	v_cmp_eq_u32_e32 vcc, v173, v169
	v_mul_f32_e32 v165, v161, v164
	s_and_b64 vcc, s[38:39], vcc
	v_fma_f32 v161, v161, v164, v203
	v_cndmask_b32_e32 v161, v165, v161, vcc
	v_cmp_le_i32_e32 vcc, v174, v169
	v_cmp_eq_u32_e64 s[100:101], v174, v169
	s_xnor_b64 vcc, vcc, s[38:39]
	s_andn2_b64 s[100:101], s[100:101], s[38:39]
	s_or_b64 vcc, vcc, s[100:101]
	v_exp_f32_e32 v157, v157
	v_sub_f32_e32 v158, v171, v158
	v_cndmask_b32_e32 v164, 0, v166, vcc
	v_mul_f32_e32 v164, v164, v226
	v_cmp_eq_u32_e32 vcc, v174, v169
	v_mul_f32_e32 v165, v162, v164
	s_and_b64 vcc, s[38:39], vcc
	v_fma_f32 v162, v162, v164, v203
	v_cndmask_b32_e32 v162, v165, v162, vcc
	v_sub_f32_e32 v166, v171, v167
	v_exp_f32_e32 v166, v166
	v_cmp_le_i32_e32 vcc, v175, v169
	v_cmp_eq_u32_e64 s[100:101], v175, v169
	s_xnor_b64 vcc, vcc, s[38:39]
	s_andn2_b64 s[100:101], s[100:101], s[38:39]
	s_or_b64 vcc, vcc, s[100:101]
	v_exp_f32_e32 v158, v158
	v_cndmask_b32_e32 v164, 0, v166, vcc
	v_mul_f32_e32 v164, v164, v227
	v_cmp_eq_u32_e32 vcc, v175, v169
	v_mul_f32_e32 v165, v163, v164
	s_and_b64 vcc, s[38:39], vcc
	v_fma_f32 v163, v163, v164, v203
	v_cndmask_b32_e32 v163, v165, v163, vcc
	v_cmp_le_i32_e32 vcc, v200, v169
	v_cmp_eq_u32_e64 s[100:101], v200, v169
	s_xnor_b64 vcc, vcc, s[38:39]
	s_andn2_b64 s[100:101], s[100:101], s[38:39]
	s_or_b64 vcc, vcc, s[100:101]
	s_mov_b32 s94, s92
	s_mov_b32 s95, s92
	v_cndmask_b32_e32 v156, 0, v156, vcc
	v_mul_f32_e32 v156, v156, v228
	v_cmp_eq_u32_e32 vcc, v200, v169
	v_mul_f32_e32 v164, v152, v156
	s_and_b64 vcc, s[38:39], vcc
	v_fma_f32 v152, v152, v156, v203
	v_cndmask_b32_e32 v156, v164, v152, vcc
	v_cmp_le_i32_e32 vcc, v201, v169
	v_cmp_eq_u32_e64 s[100:101], v201, v169
	s_xnor_b64 vcc, vcc, s[38:39]
	s_andn2_b64 s[100:101], s[100:101], s[38:39]
	s_or_b64 vcc, vcc, s[100:101]
	s_mov_b32 s93, s92
	s_nop 0
	v_cndmask_b32_e32 v152, 0, v157, vcc
	v_mul_f32_e32 v152, v152, v229
	v_cmp_eq_u32_e32 vcc, v201, v169
	v_mul_f32_e32 v157, v153, v152
	s_and_b64 vcc, s[38:39], vcc
	v_fma_f32 v152, v153, v152, v203
	v_cndmask_b32_e32 v157, v157, v152, vcc
	v_cmp_le_i32_e32 vcc, v216, v169
	v_cmp_eq_u32_e64 s[100:101], v216, v169
	s_xnor_b64 vcc, vcc, s[38:39]
	s_andn2_b64 s[100:101], s[100:101], s[38:39]
	s_or_b64 vcc, vcc, s[100:101]
	v_cndmask_b32_e32 v152, 0, v158, vcc
	v_mul_f32_e32 v152, v152, v230
	v_cmp_eq_u32_e32 vcc, v216, v169
	v_mul_f32_e32 v153, v154, v152
	s_and_b64 vcc, s[38:39], vcc
	v_fma_f32 v152, v154, v152, v203
	v_cndmask_b32_e32 v158, v153, v152, vcc
	v_sub_f32_e32 v154, v171, v159
	v_exp_f32_e32 v154, v154
	v_cmp_le_i32_e32 vcc, v217, v169
	v_cmp_eq_u32_e64 s[100:101], v217, v169
	s_xnor_b64 vcc, vcc, s[38:39]
	s_andn2_b64 s[100:101], s[100:101], s[38:39]
	s_or_b64 vcc, vcc, s[100:101]
	v_cndmask_b32_e32 v152, 0, v154, vcc
	v_mul_f32_e32 v152, v152, v231
	v_cmp_eq_u32_e32 vcc, v217, v169
	v_mul_f32_e32 v153, v155, v152
	s_and_b64 vcc, s[38:39], vcc
	v_fma_f32 v152, v155, v152, v203
	v_cndmask_b32_e32 v155, v153, v152, vcc
	v_cvt_pk_bf16_f32 v152, v160, v161
	v_cvt_pk_bf16_f32 v153, v162, v163
	v_cvt_pk_bf16_f32 v154, v156, v157
	v_cvt_pk_bf16_f32 v155, v158, v155
	ds_read_b32 v161, v214 offset:384
	v_or_b32_e32 v160, 0x60, v176
	v_mfma_f32_16x16x32_bf16 v[144:147], v[100:103], v[152:155], v[144:147]
	v_mov_b64_e32 v[102:103], s[94:95]
	v_mov_b64_e32 v[100:101], s[92:93]
	s_and_b64 vcc, exec, s[46:47]
	v_mfma_f32_16x16x32_bf16 v[140:143], v[140:143], v[152:155], v[148:151]
	s_nop 2
	v_exp_f32_e32 v148, v171
	v_add_u32_e32 v150, s5, v169
	v_ashrrev_i32_e32 v151, 31, v150
	v_lshlrev_b64 v[150:151], 13, v[150:151]
	v_pk_fma_f32 v[146:147], v[148:149], v[224:225], v[146:147] op_sel_hi:[0,1,1]
	v_pk_fma_f32 v[144:145], v[148:149], v[222:223], v[144:145] op_sel_hi:[0,1,1]
	v_pk_fma_f32 v[142:143], v[148:149], v[220:221], v[142:143] op_sel_hi:[0,1,1]
	v_pk_fma_f32 v[140:141], v[148:149], v[218:219], v[140:141] op_sel_hi:[0,1,1]
	v_lshl_add_u64 v[150:151], v[198:199], 0, v[150:151]
	v_cvt_pk_bf16_f32 v144, v144, v145
	v_cvt_pk_bf16_f32 v145, v146, v147
	v_cvt_pk_bf16_f32 v140, v140, v141
	v_cvt_pk_bf16_f32 v141, v142, v143
	global_store_dwordx2 v[150:151], v[144:145], off
	global_store_dwordx2 v[150:151], v[140:141], off offset:32
	v_lshlrev_b32_e32 v141, 8, v160
	v_mov_b64_e32 v[150:151], s[94:95]
	v_add_u32_e32 v140, s87, v141
	v_mov_b64_e32 v[148:149], s[92:93]
	s_cbranch_vccz .LBB0_536
	s_and_b64 vcc, exec, s[46:47]
	s_cbranch_vccz .LBB0_537

; #define LAS __attribute__((address_space(3)))
; template <int MODE> __device__ __forceinline__ void ssd_scan_phase(Frame& F, int j, bool ctx_out) {
;     ...
;                     const int l = 16 * lt + fr; const float cl = tab[l];
;                     f32x4 accd[2], acco[2];
;                     accd[0] = accd[1] = acco[0] = acco[1] = (f32x4){0.f, 0.f, 0.f, 0.f};
;                     const int kd = lt >> 1;
;                     if ((lt & 1) == 0) { xb_cur = xb_nxt; if (kd + 1 < 4) xb_nxt = *(const bf16x8*)(xl + (size_t)16 * T + 32 * (kd + 1)); }
;                     const bf16x8 xa = xf[0][kd], xb = xb_cur;
; #pragma unroll
;                     for (int ks = 0; ks < 4; ++ks) {
;                         const bool full = dir == 0 ? (ks < kd) : (ks > kd);
;                         if (full) {
;                             const bf16x8 gf = *(const LAS bf16x8*)(GS + l * 256 + (((4 * ks + fq) ^ fr) << 4));
;                             const float f1 = __builtin_amdgcn_exp2f(cl - tab[dir == 0 ? 32 * ks + 31 : 32 * ks]);
;                             const f32x4 z4 = (f32x4){0.f, 0.f, 0.f, 0.f};
;                             const f32x4 t0 = __builtin_amdgcn_mfma_f32_16x16x32_bf16(xs2[0][ks], gf, z4, 0, 0, 0), t1 = __builtin_amdgcn_mfma_f32_16x16x32_bf16(xs2[1][ks], gf, z4, 0, 0, 0);
;                             accd[0] += t0 * f1; accd[1] += t1 * f1;
;                         }
;                     }
; #pragma unroll
;                     for (int q = 0; q < 4; ++q) {
;                         const u32x2 lo = *(const LAS u32x2*)(CS + l * 256 + (((4 * q + (fq >> 1)) ^ fr) << 4) + (fq & 1) * 8), hi = *(const LAS u32x2*)(CS + l * 256 + (((4 * q + 2 + (fq >> 1)) ^ fr) << 4) + (fq & 1) * 8);
;                         u32x4 c4; c4.x = lo.x; c4.y = lo.y; c4.z = hi.x; c4.w = hi.y; const bf16x8 cfr = __builtin_bit_cast(bf16x8, c4);
;                         acco[0] = __builtin_amdgcn_mfma_f32_16x16x32_bf16(hf[0][q], cfr, acco[0], 0, 0, 0);
;                         acco[1] = __builtin_amdgcn_mfma_f32_16x16x32_bf16(hf[1][q], cfr, acco[1], 0, 0, 0);
;                     }
;                     {
;                         float gg[8]; unpack8(*(const LAS u32x4*)(GS + l * 256 + (((4 * kd + fq) ^ fr) << 4)), gg);
;                         const f32x4 ca = *(const LAS f32x4*)(tab + 32 * kd + 8 * fq), cb = *(const LAS f32x4*)(tab + 32 * kd + 8 * fq + 4);
.LBB0_518:
	v_add3_u32 v141, 0, v141, v195
	v_add_u32_e32 v142, v141, v185
	v_add_u32_e32 v144, v141, v183
	ds_read_b64 v[142:143], v142
	ds_read_b64 v[144:145], v144
	v_add_u32_e32 v146, v141, v187
	ds_read_b64 v[152:153], v146
	ds_read_b32 v162, v214 offset:448
	v_add_u32_e32 v146, v141, v213
	ds_read_b64 v[154:155], v146
	s_waitcnt lgkmcnt(3)
	v_mfma_f32_16x16x32_bf16 v[156:159], v[116:119], v[142:145], 0
	v_add_u32_e32 v146, v141, v212
	v_add_u32_e32 v147, v141, v211
	v_add_u32_e32 v163, v141, v191
	v_mfma_f32_16x16x32_bf16 v[142:145], v[124:127], v[142:145], 0
	ds_read_b64 v[164:165], v146
	ds_read_b64 v[166:167], v147
	ds_read_b64 v[216:217], v163
	v_add_u32_e32 v141, v141, v210
	v_lshlrev_b32_e32 v171, 4, v205
	s_waitcnt lgkmcnt(3)
	v_mfma_f32_16x16x32_bf16 v[156:159], v[112:115], v[152:155], v[156:159]
	ds_read_b64 v[218:219], v141
	v_add_u32_e32 v140, v140, v171
	v_add_u32_e32 v170, 0x61, v180
	v_mfma_f32_16x16x32_bf16 v[142:145], v[120:123], v[152:155], v[142:145]
	v_add_u32_e32 v169, 0x62, v180
	s_mov_b32 s94, s92
	s_waitcnt lgkmcnt(2)
	v_mfma_f32_16x16x32_bf16 v[152:155], v[108:111], v[164:167], v[156:159]
	s_mov_b32 s95, s92
	s_mov_b32 s93, s92
	s_nop 0
	ds_read_b128 v[156:159], v197 offset:384
	v_mfma_f32_16x16x32_bf16 v[142:145], v[128:131], v[164:167], v[142:145]
	ds_read_b128 v[164:167], v140
	s_waitcnt lgkmcnt(1)
	v_sub_f32_e32 v140, v161, v156
	v_mfma_f32_16x16x32_bf16 v[220:223], v[104:107], v[216:219], v[152:155]
	s_waitcnt lgkmcnt(0)
	v_lshlrev_b32_e32 v174, 16, v166
	v_and_b32_e32 v175, 0xffff0000, v166
	v_exp_f32_e32 v166, v140
	v_mfma_f32_16x16x32_bf16 v[216:219], v[132:135], v[216:219], v[142:145]
	ds_read_b128 v[152:155], v197 offset:896
	v_lshlrev_b32_e32 v163, 16, v164
	v_cndmask_b32_e64 v166, 0, v166, s[40:41]
	ds_read_b128 v[144:147], v197 offset:400
	v_mul_f32_e32 v163, v166, v163
	s_waitcnt lgkmcnt(1)
	v_mul_f32_e32 v166, v152, v163
	v_fma_f32 v163, v152, v163, v203
	v_lshlrev_b32_e32 v178, 16, v167
	v_and_b32_e32 v179, 0xffff0000, v167
	ds_read_b128 v[140:143], v197 offset:912
	v_cndmask_b32_e64 v197, v166, v163, s[42:43]
	v_sub_f32_e32 v167, v161, v157
	v_exp_f32_e32 v167, v167
	v_cmp_le_i32_e32 vcc, v170, v160
	v_cmp_eq_u32_e64 s[100:101], v170, v160
	s_xnor_b64 vcc, vcc, s[38:39]
	s_andn2_b64 s[100:101], s[100:101], s[38:39]
	s_or_b64 vcc, vcc, s[100:101]
	v_and_b32_e32 v164, 0xffff0000, v164
	v_sub_f32_e32 v166, v161, v158
	v_cndmask_b32_e32 v163, 0, v167, vcc
	v_mul_f32_e32 v163, v163, v164
	v_cmp_eq_u32_e32 vcc, v170, v160
	v_mul_f32_e32 v164, v153, v163
	v_fma_f32 v163, v153, v163, v203
	s_and_b64 vcc, s[38:39], vcc
	v_cndmask_b32_e32 v200, v164, v163, vcc
	v_exp_f32_e32 v166, v166
	v_lshlrev_b32_e32 v173, 16, v165
	v_add_u32_e32 v167, 0x63, v180
	v_and_b32_e32 v165, 0xffff0000, v165
	v_cmp_le_i32_e32 vcc, v169, v160
	v_cmp_eq_u32_e64 s[100:101], v169, v160
	s_xnor_b64 vcc, vcc, s[38:39]
	s_andn2_b64 s[100:101], s[100:101], s[38:39]
	s_or_b64 vcc, vcc, s[100:101]
	s_waitcnt lgkmcnt(1)
	v_sub_f32_e32 v214, v161, v145
	v_exp_f32_e32 v214, v214
	v_cndmask_b32_e32 v163, 0, v166, vcc
	v_mul_f32_e32 v163, v163, v173
	v_cmp_eq_u32_e32 vcc, v169, v160
	v_mul_f32_e32 v164, v154, v163
	v_fma_f32 v163, v154, v163, v203
	s_and_b64 vcc, s[38:39], vcc
	v_cndmask_b32_e32 v173, v164, v163, vcc
	v_sub_f32_e32 v166, v161, v159
	v_exp_f32_e32 v166, v166
	v_sub_f32_e32 v224, v161, v146
	v_exp_f32_e32 v224, v224
	v_cmp_le_i32_e32 vcc, v167, v160
	v_cmp_eq_u32_e64 s[100:101], v167, v160
	s_xnor_b64 vcc, vcc, s[38:39]
	s_andn2_b64 s[100:101], s[100:101], s[38:39]
	s_or_b64 vcc, vcc, s[100:101]
	v_sub_f32_e32 v225, v161, v147
	v_exp_f32_e32 v225, v225
	v_cndmask_b32_e32 v163, 0, v166, vcc
	v_mul_f32_e32 v163, v163, v165
	v_cmp_eq_u32_e32 vcc, v167, v160
	v_mul_f32_e32 v164, v155, v163
	v_fma_f32 v163, v155, v163, v203
	s_and_b64 vcc, s[38:39], vcc
	v_add_u32_e32 v166, 0x64, v180
	v_cndmask_b32_e32 v201, v164, v163, vcc
	v_sub_f32_e32 v165, v161, v144
	v_exp_f32_e32 v165, v165
	s_nop 1
	v_cmp_le_i32_e32 vcc, v166, v160
	v_cmp_eq_u32_e64 s[100:101], v166, v160
	s_xnor_b64 vcc, vcc, s[38:39]
	s_andn2_b64 s[100:101], s[100:101], s[38:39]
	s_or_b64 vcc, vcc, s[100:101]
	v_cndmask_b32_e32 v163, 0, v165, vcc
	v_mul_f32_e32 v163, v163, v174
	v_cmp_eq_u32_e32 vcc, v166, v160
	s_waitcnt lgkmcnt(0)
; __device__ __forceinline__ unsigned cvt_pk_bf16(float lo, float hi) { const f32x2 v = {lo, hi}; return __builtin_bit_cast(unsigned, __builtin_convertvector(v, bf16x2_t)); }
; __device__ __forceinline__ u32x4 pack8(const float (&f)[8]) { u32x4 w; w.x = cvt_pk_bf16(f[0], f[1]); w.y = cvt_pk_bf16(f[2], f[3]); w.z = cvt_pk_bf16(f[4], f[5]); w.w = cvt_pk_bf16(f[6], f[7]); return w; }
; template <int MODE> __device__ __forceinline__ void ssd_scan_phase(Frame& F, int j, bool ctx_out) {
;     ...
;                         for (int jj = 0; jj < 8; ++jj) { const int s = 32 * kd + 8 * fq + jj; const bool valid = dir == 0 ? (s <= l) : (s >= l);
;                             const float e = valid ? __builtin_amdgcn_exp2f(cl - cs[jj]) : 0.f; m[jj] = gg[jj] * e * ds[jj]; if (dir == 0 && s == l) m[jj] += dsk; }
;                         const bf16x8 mf = __builtin_bit_cast(bf16x8, pack8(m));
;                         accd[0] = __builtin_amdgcn_mfma_f32_16x16x32_bf16(xa, mf, accd[0], 0, 0, 0);
;                         accd[1] = __builtin_amdgcn_mfma_f32_16x16x32_bf16(xb, mf, accd[1], 0, 0, 0);
;                     }
;                     const float el = __builtin_amdgcn_exp2f(cl);
; #pragma unroll
;                     for (int pt = 0; pt < 2; ++pt) { const f32x4 y = accd[pt] + acco[pt] * el; u32x2 o; o.x = cvt_pk_bf16(y[0], y[1]); o.y = cvt_pk_bf16(y[2], y[3]);
;                         *(u32x2*)(yout + (size_t)(row0 + l) * DI + h * 64 + ph * 32 + 16 * pt + 4 * fq) = o; }
;                 }
	v_mul_f32_e32 v164, v140, v163
	v_fma_f32 v163, v140, v163, v203
	s_and_b64 vcc, s[38:39], vcc
	v_add_u32_e32 v165, 0x65, v180
	v_cndmask_b32_e32 v174, v164, v163, vcc
	s_nop 1
	s_nop 1
	v_cmp_le_i32_e32 vcc, v165, v160
	v_cmp_eq_u32_e64 s[100:101], v165, v160
	s_xnor_b64 vcc, vcc, s[38:39]
	s_andn2_b64 s[100:101], s[100:101], s[38:39]
	s_or_b64 vcc, vcc, s[100:101]
	v_cndmask_b32_e32 v163, 0, v214, vcc
	v_mul_f32_e32 v163, v163, v175
	v_cmp_eq_u32_e32 vcc, v165, v160
	v_mul_f32_e32 v164, v141, v163
	v_fma_f32 v163, v141, v163, v203
	s_and_b64 vcc, s[38:39], vcc
	v_cndmask_b32_e32 v175, v164, v163, vcc
	v_add_u32_e32 v164, 0x66, v180
	v_cvt_pk_bf16_f32 v226, v174, v175
	v_exp_f32_e32 v174, v161
	s_nop 1
	v_cmp_le_i32_e32 vcc, v164, v160
	v_cmp_eq_u32_e64 s[100:101], v164, v160
	s_xnor_b64 vcc, vcc, s[38:39]
	s_andn2_b64 s[100:101], s[100:101], s[38:39]
	s_or_b64 vcc, vcc, s[100:101]
	v_cndmask_b32_e32 v163, 0, v224, vcc
	v_mul_f32_e32 v163, v163, v178
	v_cmp_eq_u32_e32 vcc, v164, v160
	v_mul_f32_e32 v178, v142, v163
	v_fma_f32 v163, v142, v163, v203
	s_and_b64 vcc, s[38:39], vcc
	v_cndmask_b32_e32 v178, v178, v163, vcc
	v_add_u32_e32 v163, 0x67, v180
	s_nop 1
	s_nop 1
	v_cmp_le_i32_e32 vcc, v163, v160
	v_cmp_eq_u32_e64 s[100:101], v163, v160
	s_xnor_b64 vcc, vcc, s[38:39]
	s_andn2_b64 s[100:101], s[100:101], s[38:39]
	s_or_b64 vcc, vcc, s[100:101]
	v_cvt_pk_bf16_f32 v224, v197, v200
	s_nop 0
	v_cndmask_b32_e32 v214, 0, v225, vcc
	v_mul_f32_e32 v179, v214, v179
	v_cmp_eq_u32_e32 vcc, v163, v160
	v_mul_f32_e32 v214, v143, v179
	v_fma_f32 v179, v143, v179, v203
	s_and_b64 vcc, s[38:39], vcc
	v_cndmask_b32_e32 v179, v214, v179, vcc
	v_cvt_pk_bf16_f32 v225, v173, v201
	v_cvt_pk_bf16_f32 v227, v178, v179
	v_add_u32_e32 v160, s5, v160
	v_ashrrev_i32_e32 v161, 31, v160
	v_mfma_f32_16x16x32_bf16 v[228:231], v[8:11], v[224:227], v[148:151]
	v_lshlrev_b64 v[160:161], 13, v[160:161]
	v_lshl_add_u64 v[160:161], v[198:199], 0, v[160:161]
	s_and_b64 vcc, exec, s[46:47]
	s_waitcnt vmcnt(6)
	v_mfma_f32_16x16x32_bf16 v[100:103], v[136:139], v[224:227], v[100:103]
	v_mov_b64_e32 v[150:151], s[94:95]
	s_nop 1
	v_pk_fma_f32 v[200:201], v[174:175], v[222:223], v[230:231] op_sel_hi:[0,1,1]
	v_pk_fma_f32 v[220:221], v[174:175], v[220:221], v[228:229] op_sel_hi:[0,1,1]
	v_cvt_pk_bf16_f32 v220, v220, v221
	v_cvt_pk_bf16_f32 v221, v200, v201
	s_nop 0
	v_pk_fma_f32 v[102:103], v[174:175], v[218:219], v[102:103] op_sel_hi:[0,1,1]
	v_pk_fma_f32 v[100:101], v[174:175], v[216:217], v[100:101] op_sel_hi:[0,1,1]
	v_cvt_pk_bf16_f32 v100, v100, v101
	v_cvt_pk_bf16_f32 v101, v102, v103
	global_store_dwordx2 v[160:161], v[220:221], off
	global_store_dwordx2 v[160:161], v[100:101], off offset:32
	v_or_b32_e32 v160, 0x70, v176
	v_lshlrev_b32_e32 v173, 8, v160
	v_mov_b64_e32 v[102:103], s[94:95]
	v_mov_b64_e32 v[148:149], s[92:93]
	v_add_u32_e32 v161, s87, v173
	v_mov_b64_e32 v[100:101], s[92:93]
	s_cbranch_vccz .LBB0_538
	s_and_b64 vcc, exec, s[46:47]
	s_cbranch_vccz .LBB0_539
